# row phases: non-temporal hint on the once-read streaming loads (x, mix, ff, out)
# baseline (speedup 1.0000x reference)
; __device__ __forceinline__ void ph_rowsA(int tbase) {
;     ...
;     for (int m = gw; m < TG; m += NGW) {
;         const int tp = pb + m, bp = tp >> 12, tc = tbase + m, bc = tc >> 12;
;         const f32x4* xr = (const f32x4*)(x + (size_t)tc * 1024) + lane; f32x4 v[4], ov[4]; u32x2 fw[4];
; #pragma unroll
;         for (int j = 0; j < 4; ++j) { v[j] = xr[64 * j]; const int c0 = 4 * lane + 256 * j; fw[j] = *(const u32x2*)(FF + (size_t)m * 1024 + c0); ov[j] = *(const f32x4*)(out + (size_t)tp * 1024 + c0); }
;         float sv = lane < 16 ? SSQ_FF[lane * TT + tp] : 0.f;
.LBB0_173:
	v_lshl_add_u64 v[2:3], s[80:81], 0, v[40:41]
	v_lshl_add_u64 v[42:43], s[72:73], 0, v[40:41]
	global_load_dwordx4 v[26:29], v[2:3], off nt
	global_load_dwordx4 v[18:21], v[2:3], off offset:1024 nt
	global_load_dwordx4 v[30:33], v[42:43], off nt
	global_load_dwordx4 v[22:25], v[42:43], off offset:1024 nt
	global_load_dwordx4 v[10:13], v[2:3], off offset:2048 nt
	s_nop 0
	global_load_dwordx4 v[2:5], v[2:3], off offset:3072 nt
	s_nop 0
	global_load_dwordx2 v[50:51], v[38:39], off nt
	global_load_dwordx2 v[48:49], v[38:39], off offset:512 nt
	global_load_dwordx2 v[46:47], v[38:39], off offset:1024 nt
	global_load_dwordx2 v[44:45], v[38:39], off offset:1536 nt
	global_load_dwordx4 v[14:17], v[42:43], off offset:2048 nt
	global_load_dwordx4 v[6:9], v[42:43], off offset:3072 nt
	v_mov_b32_e32 v0, 0
	s_and_saveexec_b64 s[8:9], vcc
	s_cbranch_execz .LBB0_172
	v_add_u32_e32 v64, s4, v58
	v_ashrrev_i32_e32 v65, 31, v64
	v_lshl_add_u64 v[64:65], v[64:65], 2, s[42:43]
	global_load_dword v0, v[64:65], off
	s_branch .LBB0_172

; __device__ __forceinline__ unsigned pk2(float lo, float hi) { const f32x2 v = {lo, hi}; const bf16x2_t b = __builtin_convertvector(v, bf16x2_t); return __builtin_bit_cast(unsigned, b); }
; __device__ __forceinline__ float dot4(f32x4 a) { return (a[0] * a[0] + a[1] * a[1]) + (a[2] * a[2] + a[3] * a[3]); }
; __device__ __forceinline__ void ph_hrows(int tbase) {
;     ...
;     for (int m = gw; m < TG; m += NGW) { const int t = tbase + m, b = t >> 12;
;         const f32x4* xr = (const f32x4*)(x + (size_t)t * 1024) + lane; f32x4 v[4]; float s = 0.f;
; #pragma unroll
;         for (int j = 0; j < 4; ++j) { v[j] = xr[64 * j]; s += dot4(v[j]); }
;         const float rs = rsqrtf(wave_sum(s) * (1.f / 1024.f) + EPS); const float* shift = MOD + b * 6144; const float* scale = shift + 1024;
; #pragma unroll
;         for (int j = 0; j < 4; ++j) { const int c0 = 4 * lane + 256 * j; const f32x4 g = *(const f32x4*)(g_pre_mix + c0), sc = *(const f32x4*)(scale + c0), sh = *(const f32x4*)(shift + c0);
;             const f32x4 hv = v[j] * rs * g * (sc + 1.f) + sh; u32x2 w; w.x = pk2(hv[0], hv[1]); w.y = pk2(hv[2], hv[3]); *(u32x2*)(H + (size_t)m * 1024 + c0) = w; } }
.LBB0_179:
	global_load_dwordx4 v[18:21], v[6:7], off offset:-2048 nt
	global_load_dwordx4 v[22:25], v[6:7], off offset:-1024 nt
	global_load_dwordx4 v[26:29], v[6:7], off offset:1024 nt
	global_load_dwordx4 v[30:33], v[6:7], off nt
	s_ashr_i32 s5, s4, 12
	s_mul_i32 s12, s5, 0x1800
	s_ashr_i32 s13, s12, 31
	s_lshl_b64 s[12:13], s[12:13], 2
	s_add_u32 s12, s2, s12
	s_addc_u32 s13, s16, s13
	s_add_u32 s14, s12, 0x1000
	global_load_dwordx4 v[34:37], v[2:3], off
	s_addc_u32 s15, s13, 0
	global_load_dwordx4 v[38:41], v0, s[14:15]
	global_load_dwordx4 v[42:45], v0, s[12:13]
	s_add_i32 s4, s4, s6
	v_lshl_add_u64 v[6:7], v[6:7], 0, s[10:11]
	s_cmpk_gt_i32 s4, 0x3fff
	s_waitcnt vmcnt(6)
	v_pk_mul_f32 v[46:47], v[20:21], v[20:21]
	v_pk_mul_f32 v[48:49], v[18:19], v[18:19]
	s_waitcnt vmcnt(5)
	v_pk_mul_f32 v[50:51], v[24:25], v[24:25]
	v_pk_mul_f32 v[52:53], v[22:23], v[22:23]
	v_pk_mov_b32 v[58:59], v[48:49], v[46:47] op_sel:[1,0]
	v_mov_b32_e32 v49, v47
	v_pk_mov_b32 v[46:47], v[52:53], v[50:51] op_sel:[1,0]
	v_mov_b32_e32 v53, v51
	s_waitcnt vmcnt(4)
	v_mul_f32_e32 v57, v27, v27
	s_waitcnt vmcnt(3)
	v_mul_f32_e32 v54, v31, v31
	v_mul_f32_e32 v56, v33, v33
	v_pk_add_f32 v[48:49], v[58:59], v[48:49]
	v_pk_add_f32 v[46:47], v[46:47], v[52:53]
	v_mul_f32_e32 v17, v26, v26
	v_mul_f32_e32 v60, v28, v28
	v_mul_f32_e32 v61, v29, v29
	v_pk_fma_f32 v[50:51], v[30:31], v[30:31], v[54:55] op_sel_hi:[1,1,0]
	v_pk_fma_f32 v[54:55], v[32:33], v[32:33], v[56:57] op_sel_hi:[1,1,0]
	v_pk_add_f32 v[48:49], v[48:49], v[48:49] op_sel:[0,1] op_sel_hi:[1,0]
	v_pk_add_f32 v[46:47], v[46:47], v[46:47] op_sel:[0,1] op_sel_hi:[1,0]
	v_mov_b32_e32 v51, v60
	v_mov_b32_e32 v55, v61
	v_mov_b32_e32 v49, v17
	v_mov_b32_e32 v47, v57
	v_pk_add_f32 v[50:51], v[50:51], v[54:55]
	v_pk_add_f32 v[46:47], v[48:49], v[46:47]
	s_waitcnt vmcnt(1)
	v_pk_add_f32 v[40:41], v[40:41], 1.0 op_sel_hi:[1,0]
	v_pk_add_f32 v[46:47], v[46:47], v[50:51]
	v_pk_add_f32 v[38:39], v[38:39], 1.0 op_sel_hi:[1,0]
	v_add_f32_e32 v17, v46, v47
	ds_bpermute_b32 v46, v8, v17
	s_waitcnt lgkmcnt(0)
	v_add_f32_e32 v17, v17, v46
	ds_bpermute_b32 v46, v9, v17
	s_waitcnt lgkmcnt(0)
	v_add_f32_e32 v17, v17, v46
	ds_bpermute_b32 v46, v10, v17
	s_waitcnt lgkmcnt(0)
	v_add_f32_e32 v17, v17, v46
	ds_bpermute_b32 v46, v11, v17
	s_waitcnt lgkmcnt(0)
	v_add_f32_e32 v17, v17, v46
	ds_bpermute_b32 v46, v12, v17
	s_waitcnt lgkmcnt(0)
	v_add_f32_e32 v17, v17, v46
	ds_bpermute_b32 v46, v13, v17
	s_waitcnt lgkmcnt(0)
	v_add_f32_e32 v17, v17, v46
	v_fmamk_f32 v17, v17, 0x3a800000, v220
	v_mul_f32_e32 v46, 0x4b800000, v17
	v_cmp_gt_f32_e32 vcc, s51, v17
	s_nop 1
	v_cndmask_b32_e32 v17, v17, v46, vcc
	v_rsq_f32_e32 v17, v17
	s_nop 0
	v_mul_f32_e32 v46, 0x45800000, v17
	v_cndmask_b32_e32 v46, v17, v46, vcc
	v_pk_mul_f32 v[20:21], v[20:21], v[46:47] op_sel_hi:[1,0]
	v_pk_mul_f32 v[18:19], v[18:19], v[46:47] op_sel_hi:[1,0]
	v_pk_mul_f32 v[20:21], v[36:37], v[20:21]
	v_pk_mul_f32 v[18:19], v[34:35], v[18:19]
	s_waitcnt vmcnt(0)
	v_pk_fma_f32 v[20:21], v[40:41], v[20:21], v[44:45]
	v_pk_fma_f32 v[18:19], v[38:39], v[18:19], v[42:43]
	v_pk_mul_f32 v[24:25], v[24:25], v[46:47] op_sel_hi:[1,0]
	v_cvt_pk_bf16_f32 v18, v18, v19
	v_cvt_pk_bf16_f32 v19, v20, v21
	global_store_dwordx2 v[4:5], v[18:19], off
	global_load_dwordx4 v[18:21], v[2:3], off offset:1024
	s_nop 0
	global_load_dwordx4 v[34:37], v14, s[14:15]
	global_load_dwordx4 v[38:41], v0, s[12:13] offset:1024
	v_pk_mul_f32 v[22:23], v[22:23], v[46:47] op_sel_hi:[1,0]
	v_pk_mul_f32 v[32:33], v[32:33], v[46:47] op_sel_hi:[1,0]
	v_pk_mul_f32 v[30:31], v[30:31], v[46:47] op_sel_hi:[1,0]
	v_pk_mul_f32 v[28:29], v[28:29], v[46:47] op_sel_hi:[1,0]
	v_pk_mul_f32 v[26:27], v[26:27], v[46:47] op_sel_hi:[1,0]
	s_waitcnt vmcnt(2)
	v_pk_mul_f32 v[18:19], v[18:19], v[22:23]
	v_pk_mul_f32 v[20:21], v[20:21], v[24:25]
	s_waitcnt vmcnt(1)
	v_pk_add_f32 v[22:23], v[36:37], 1.0 op_sel_hi:[1,0]
	v_pk_add_f32 v[24:25], v[34:35], 1.0 op_sel_hi:[1,0]
	s_waitcnt vmcnt(0)
	v_pk_fma_f32 v[20:21], v[22:23], v[20:21], v[40:41]
	v_pk_fma_f32 v[18:19], v[24:25], v[18:19], v[38:39]
	s_nop 0
	v_cvt_pk_bf16_f32 v18, v18, v19
	v_cvt_pk_bf16_f32 v19, v20, v21
	global_store_dwordx2 v[4:5], v[18:19], off offset:512
	global_load_dwordx4 v[18:21], v[2:3], off offset:2048
	s_nop 0
	global_load_dwordx4 v[22:25], v15, s[14:15]
	global_load_dwordx4 v[34:37], v0, s[12:13] offset:2048
	s_waitcnt vmcnt(2)
	v_pk_mul_f32 v[18:19], v[18:19], v[30:31]
	v_pk_mul_f32 v[20:21], v[20:21], v[32:33]
	s_waitcnt vmcnt(1)
	v_pk_add_f32 v[24:25], v[24:25], 1.0 op_sel_hi:[1,0]
	v_pk_add_f32 v[22:23], v[22:23], 1.0 op_sel_hi:[1,0]
	s_waitcnt vmcnt(0)
	v_pk_fma_f32 v[20:21], v[24:25], v[20:21], v[36:37]
	v_pk_fma_f32 v[18:19], v[22:23], v[18:19], v[34:35]
	s_nop 0
	v_cvt_pk_bf16_f32 v18, v18, v19
	v_cvt_pk_bf16_f32 v19, v20, v21
	global_store_dwordx2 v[4:5], v[18:19], off offset:1024
	global_load_dwordx4 v[18:21], v[2:3], off offset:3072
	s_nop 0
	global_load_dwordx4 v[22:25], v16, s[14:15]
	global_load_dwordx4 v[30:33], v0, s[12:13] offset:3072
	s_waitcnt vmcnt(2)
	v_pk_mul_f32 v[18:19], v[18:19], v[26:27]
	v_pk_mul_f32 v[20:21], v[20:21], v[28:29]
	s_waitcnt vmcnt(1)
	v_pk_add_f32 v[24:25], v[24:25], 1.0 op_sel_hi:[1,0]
	v_pk_add_f32 v[22:23], v[22:23], 1.0 op_sel_hi:[1,0]
	s_waitcnt vmcnt(0)
	v_pk_fma_f32 v[20:21], v[24:25], v[20:21], v[32:33]
	v_pk_fma_f32 v[18:19], v[22:23], v[18:19], v[30:31]
	s_nop 0
	v_cvt_pk_bf16_f32 v18, v18, v19
	v_cvt_pk_bf16_f32 v19, v20, v21
	global_store_dwordx2 v[4:5], v[18:19], off offset:1536
	v_lshl_add_u64 v[4:5], v[4:5], 0, s[8:9]
	s_cbranch_scc0 .LBB0_179

; __device__ __forceinline__ float dot4(f32x4 a) { return (a[0] * a[0] + a[1] * a[1]) + (a[2] * a[2] + a[3] * a[3]); }
; __device__ __forceinline__ void ph_x1rows(int tbase) {
;     ...
;     for (int m = gw; m < TG; m += NGW) { const int t = tbase + m, b = t >> 12;
;         float sv = lane < 16 ? SSQ_MIX[lane * TT + t] : 0.f; sv += __shfl_xor(sv, 1); sv += __shfl_xor(sv, 2); sv += __shfl_xor(sv, 4); sv += __shfl_xor(sv, 8); sv = __shfl(sv, 0);
;         const float rs1 = rsqrtf(sv * (1.f / 1024.f) + EPS); const float* mod = MOD + b * 6144;
;         f32x4 v[4]; float s = 0.f;
; #pragma unroll
;         for (int j = 0; j < 4; ++j) { const int c0 = 4 * lane + 256 * j; const u32x2 w = *(const u32x2*)(MIX + (size_t)m * 1024 + c0);
;             const f32x4 f = {bflo(w.x), bfhi(w.x), bflo(w.y), bfhi(w.y)}; const f32x4 g = *(const f32x4*)(g_post_mix + c0), ga = *(const f32x4*)(mod + 2048 + c0);
;             v[j] = *(const f32x4*)(x + (size_t)t * 1024 + c0) + ga * (f * rs1 * g); *(f32x4*)(out + (size_t)t * 1024 + c0) = v[j]; s += dot4(v[j]); }
.LBB0_1217:
	s_or_b64 exec, exec, s[8:9]
	s_waitcnt vmcnt(0)
	ds_bpermute_b32 v2, v30, v0
	s_add_i32 s10, s63, s4
	s_ashr_i32 s2, s10, 12
	s_mul_i32 s8, s2, 0x1800
	s_ashr_i32 s9, s8, 31
	s_waitcnt lgkmcnt(0)
	v_add_f32_e32 v0, v0, v2
	ds_bpermute_b32 v2, v31, v0
	s_lshl_b64 s[8:9], s[8:9], 2
	s_add_u32 s5, s12, s8
	s_addc_u32 s7, s13, s9
	s_add_u32 s8, s5, 0x2000
	s_waitcnt lgkmcnt(0)
	v_add_f32_e32 v0, v0, v2
	ds_bpermute_b32 v2, v32, v0
	s_addc_u32 s9, s7, 0
	s_ashr_i32 s11, s10, 31
	s_lshl_b64 s[10:11], s[10:11], 12
	v_lshl_add_u64 v[6:7], v[22:23], 0, s[10:11]
	s_waitcnt lgkmcnt(0)
	v_add_f32_e32 v0, v0, v2
	ds_bpermute_b32 v2, v33, v0
	s_add_u32 s64, s5, 0x4000
	s_addc_u32 s65, s7, 0
	s_add_u32 s72, s5, 0x3000
	s_addc_u32 s73, s7, 0
	s_waitcnt lgkmcnt(0)
	v_add_f32_e32 v0, v0, v2
	ds_bpermute_b32 v0, v244, v0
	s_mov_b32 s2, 0xe7c00000
	s_add_i32 s4, s4, s6
	s_cmpk_lt_i32 s4, 0x4000
	s_waitcnt lgkmcnt(0)
	v_fmamk_f32 v0, v0, 0x3a800000, v220
	v_cmp_gt_f32_e64 s[38:39], s51, v0
	v_mul_f32_e32 v2, 0x4b800000, v0
	s_nop 0
	v_cndmask_b32_e64 v0, v0, v2, s[38:39]
	v_rsq_f32_e32 v0, v0
	s_nop 0
	v_mul_f32_e32 v2, 0x45800000, v0
	v_cndmask_b32_e64 v0, v0, v2, s[38:39]
	global_load_dwordx2 v[2:3], v[26:27], off nt
	s_waitcnt vmcnt(0)
	v_lshlrev_b32_e32 v16, 16, v2
	v_and_b32_e32 v17, 0xffff0000, v2
	v_lshlrev_b32_e32 v28, 16, v3
	v_and_b32_e32 v29, 0xffff0000, v3
	global_load_dwordx4 v[2:5], v[20:21], off
	global_load_dwordx4 v[8:11], v37, s[8:9]
	global_load_dwordx4 v[12:15], v[6:7], off nt
	v_pk_mul_f32 v[28:29], v[0:1], v[28:29] op_sel_hi:[0,1]
	v_pk_mul_f32 v[16:17], v[0:1], v[16:17] op_sel_hi:[0,1]
	s_waitcnt vmcnt(2)
	v_pk_mul_f32 v[2:3], v[2:3], v[16:17]
	v_pk_mul_f32 v[4:5], v[4:5], v[28:29]
	v_lshl_add_u64 v[28:29], v[24:25], 0, s[10:11]
	s_waitcnt vmcnt(0)
	v_pk_fma_f32 v[16:17], v[10:11], v[4:5], v[14:15]
	v_pk_fma_f32 v[14:15], v[8:9], v[2:3], v[12:13]
	global_store_dwordx4 v[28:29], v[14:17], off
	v_pk_mul_f32 v[2:3], v[16:17], v[16:17]
	v_pk_mul_f32 v[4:5], v[14:15], v[14:15]
	s_nop 0
	v_pk_mov_b32 v[8:9], v[4:5], v[2:3] op_sel:[1,0]
	v_mov_b32_e32 v5, v3
	global_load_dwordx2 v[2:3], v[26:27], off offset:512 nt
	v_pk_add_f32 v[50:51], v[8:9], v[4:5]
	s_waitcnt vmcnt(0)
	v_lshlrev_b32_e32 v12, 16, v2
	v_and_b32_e32 v13, 0xffff0000, v2
	v_lshlrev_b32_e32 v46, 16, v3
	v_and_b32_e32 v47, 0xffff0000, v3
	global_load_dwordx4 v[2:5], v[20:21], off offset:1024
	global_load_dwordx4 v[8:11], v38, s[8:9]
	global_load_dwordx4 v[42:45], v[6:7], off offset:1024 nt
	v_pk_mul_f32 v[46:47], v[0:1], v[46:47] op_sel_hi:[0,1]
	v_pk_mul_f32 v[12:13], v[0:1], v[12:13] op_sel_hi:[0,1]
	s_waitcnt vmcnt(2)
	v_pk_mul_f32 v[2:3], v[2:3], v[12:13]
	v_pk_mul_f32 v[4:5], v[4:5], v[46:47]
	s_waitcnt vmcnt(0)
	v_pk_fma_f32 v[12:13], v[10:11], v[4:5], v[44:45]
	v_pk_fma_f32 v[10:11], v[8:9], v[2:3], v[42:43]
	global_store_dwordx4 v[28:29], v[10:13], off offset:1024
	v_pk_mul_f32 v[2:3], v[12:13], v[12:13]
	v_pk_mul_f32 v[4:5], v[10:11], v[10:11]
	s_nop 0
	v_pk_mov_b32 v[8:9], v[4:5], v[2:3] op_sel:[1,0]
	v_mov_b32_e32 v5, v3
	global_load_dwordx2 v[2:3], v[26:27], off offset:1024 nt
	v_pk_add_f32 v[52:53], v[8:9], v[4:5]
	s_waitcnt vmcnt(0)
	v_lshlrev_b32_e32 v8, 16, v2
	v_and_b32_e32 v9, 0xffff0000, v2
	v_lshlrev_b32_e32 v54, 16, v3
	v_and_b32_e32 v55, 0xffff0000, v3
	global_load_dwordx4 v[2:5], v[20:21], off offset:2048
	global_load_dwordx4 v[42:45], v39, s[8:9]
	global_load_dwordx4 v[46:49], v[6:7], off offset:2048 nt
	v_pk_mul_f32 v[54:55], v[0:1], v[54:55] op_sel_hi:[0,1]
	v_pk_mul_f32 v[8:9], v[0:1], v[8:9] op_sel_hi:[0,1]
	s_waitcnt vmcnt(2)
	v_pk_mul_f32 v[2:3], v[2:3], v[8:9]
	v_pk_mul_f32 v[4:5], v[4:5], v[54:55]
	s_waitcnt vmcnt(0)
	v_pk_fma_f32 v[2:3], v[42:43], v[2:3], v[46:47]
	v_pk_fma_f32 v[4:5], v[44:45], v[4:5], v[48:49]
	global_store_dwordx4 v[28:29], v[2:5], off offset:2048
	global_load_dwordx2 v[8:9], v[26:27], off offset:1536 nt
	s_waitcnt vmcnt(0)
	v_lshlrev_b32_e32 v54, 16, v8
	v_and_b32_e32 v55, 0xffff0000, v8
	v_lshlrev_b32_e32 v56, 16, v9
	v_and_b32_e32 v57, 0xffff0000, v9
	global_load_dwordx4 v[42:45], v[20:21], off offset:3072
	global_load_dwordx4 v[46:49], v40, s[8:9]
	s_nop 0
	global_load_dwordx4 v[6:9], v[6:7], off offset:3072 nt
	v_pk_mul_f32 v[56:57], v[0:1], v[56:57] op_sel_hi:[0,1]
	v_pk_mul_f32 v[54:55], v[0:1], v[54:55] op_sel_hi:[0,1]
	s_waitcnt vmcnt(2)
	v_pk_mul_f32 v[42:43], v[42:43], v[54:55]
	v_pk_mul_f32 v[44:45], v[44:45], v[56:57]
	s_waitcnt vmcnt(0)
; __device__ __forceinline__ unsigned pk2(float lo, float hi) { const f32x2 v = {lo, hi}; const bf16x2_t b = __builtin_convertvector(v, bf16x2_t); return __builtin_bit_cast(unsigned, b); }
; __device__ __forceinline__ float dot4(f32x4 a) { return (a[0] * a[0] + a[1] * a[1]) + (a[2] * a[2] + a[3] * a[3]); }
; __device__ __forceinline__ void ph_x1rows(int tbase) {
;     ...
;             v[j] = *(const f32x4*)(x + (size_t)t * 1024 + c0) + ga * (f * rs1 * g); *(f32x4*)(out + (size_t)t * 1024 + c0) = v[j]; s += dot4(v[j]); }
;         const float rs2 = rsqrtf(wave_sum(s) * (1.f / 1024.f) + EPS);
; #pragma unroll
;         for (int j = 0; j < 4; ++j) { const int c0 = 4 * lane + 256 * j; const f32x4 g = *(const f32x4*)(g_pre_mlp + c0), sc = *(const f32x4*)(mod + 4096 + c0), sh = *(const f32x4*)(mod + 3072 + c0);
;             const f32x4 hv = v[j] * rs2 * g * (sc + 1.f) + sh; u32x2 w; w.x = pk2(hv[0], hv[1]); w.y = pk2(hv[2], hv[3]); *(u32x2*)(H + (size_t)m * 1024 + c0) = w; } }
	v_pk_fma_f32 v[6:7], v[46:47], v[42:43], v[6:7]
	v_pk_fma_f32 v[8:9], v[48:49], v[44:45], v[8:9]
	global_store_dwordx4 v[28:29], v[6:9], off offset:3072
	v_mul_f32_e32 v0, v6, v6
	v_mul_f32_e32 v41, v7, v7
	v_pk_add_f32 v[28:29], v[50:51], v[50:51] op_sel:[0,1] op_sel_hi:[1,0]
	v_pk_add_f32 v[42:43], v[52:53], v[52:53] op_sel:[0,1] op_sel_hi:[1,0]
	v_mov_b32_e32 v29, v0
	v_mov_b32_e32 v43, v41
	v_mul_f32_e32 v0, v3, v3
	v_mul_f32_e32 v44, v8, v8
	v_pk_add_f32 v[28:29], v[28:29], v[42:43]
	v_pk_fma_f32 v[42:43], v[2:3], v[2:3], v[0:1] op_sel_hi:[1,1,0]
	v_mul_f32_e32 v0, v5, v5
	v_mul_f32_e32 v46, v9, v9
	v_mov_b32_e32 v43, v44
	v_pk_fma_f32 v[44:45], v[4:5], v[4:5], v[0:1] op_sel_hi:[1,1,0]
	s_nop 0
	v_mov_b32_e32 v45, v46
	v_pk_add_f32 v[42:43], v[42:43], v[44:45]
	s_nop 0
	v_pk_add_f32 v[28:29], v[28:29], v[42:43]
	global_load_dwordx4 v[42:45], v[18:19], off
	global_load_dwordx4 v[46:49], v37, s[64:65]
	global_load_dwordx4 v[50:53], v37, s[72:73]
	v_add_f32_e32 v0, v28, v29
	ds_bpermute_b32 v28, v30, v0
	s_waitcnt lgkmcnt(0)
	v_add_f32_e32 v0, v0, v28
	ds_bpermute_b32 v28, v31, v0
	s_waitcnt lgkmcnt(0)
	v_add_f32_e32 v0, v0, v28
	ds_bpermute_b32 v28, v32, v0
	s_waitcnt lgkmcnt(0)
	v_add_f32_e32 v0, v0, v28
	ds_bpermute_b32 v28, v33, v0
	s_waitcnt lgkmcnt(0)
	v_add_f32_e32 v0, v0, v28
	ds_bpermute_b32 v28, v34, v0
	s_waitcnt lgkmcnt(0)
	v_add_f32_e32 v0, v0, v28
	ds_bpermute_b32 v28, v35, v0
	s_waitcnt lgkmcnt(0)
	v_add_f32_e32 v0, v0, v28
	v_fmamk_f32 v0, v0, 0x3a800000, v220
	v_cmp_gt_f32_e64 s[38:39], s51, v0
	v_mul_f32_e32 v28, 0x4b800000, v0
	s_nop 0
	v_cndmask_b32_e64 v0, v0, v28, s[38:39]
	v_rsq_f32_e32 v0, v0
	s_nop 0
	v_mul_f32_e32 v28, 0x45800000, v0
	v_cndmask_b32_e64 v0, v0, v28, s[38:39]
	v_pk_mul_f32 v[16:17], v[16:17], v[0:1] op_sel_hi:[1,0]
	v_pk_mul_f32 v[14:15], v[14:15], v[0:1] op_sel_hi:[1,0]
	v_pk_mul_f32 v[12:13], v[12:13], v[0:1] op_sel_hi:[1,0]
	v_pk_mul_f32 v[10:11], v[10:11], v[0:1] op_sel_hi:[1,0]
	v_pk_mul_f32 v[4:5], v[4:5], v[0:1] op_sel_hi:[1,0]
	v_pk_mul_f32 v[2:3], v[2:3], v[0:1] op_sel_hi:[1,0]
	v_pk_mul_f32 v[8:9], v[8:9], v[0:1] op_sel_hi:[1,0]
	v_pk_mul_f32 v[6:7], v[6:7], v[0:1] op_sel_hi:[1,0]
	s_waitcnt vmcnt(2)
	v_pk_mul_f32 v[14:15], v[42:43], v[14:15]
	v_pk_mul_f32 v[16:17], v[44:45], v[16:17]
	s_waitcnt vmcnt(1)
	v_pk_add_f32 v[28:29], v[48:49], 1.0 op_sel_hi:[1,0]
	v_pk_add_f32 v[42:43], v[46:47], 1.0 op_sel_hi:[1,0]
	s_waitcnt vmcnt(0)
	v_pk_fma_f32 v[16:17], v[28:29], v[16:17], v[52:53]
	v_pk_fma_f32 v[14:15], v[42:43], v[14:15], v[50:51]
	s_nop 0
	v_cvt_pk_bf16_f32 v14, v14, v15
	v_cvt_pk_bf16_f32 v15, v16, v17
	v_add_co_u32_e64 v16, s[38:39], s2, v26
	s_mov_b32 s2, 0xe7c01000
	s_nop 0
	v_addc_co_u32_e64 v17, s[38:39], -1, v27, s[38:39]
	global_store_dwordx2 v[16:17], v[14:15], off
	global_load_dwordx4 v[14:17], v[18:19], off offset:1024
	s_nop 0
	global_load_dwordx4 v[42:45], v38, s[64:65]
	global_load_dwordx4 v[46:49], v38, s[72:73]
	v_add_co_u32_e64 v28, s[38:39], s2, v26
	s_waitcnt vmcnt(2)
	v_pk_mul_f32 v[10:11], v[14:15], v[10:11]
	v_pk_mul_f32 v[12:13], v[16:17], v[12:13]
	s_waitcnt vmcnt(1)
	v_pk_add_f32 v[14:15], v[44:45], 1.0 op_sel_hi:[1,0]
	v_pk_add_f32 v[16:17], v[42:43], 1.0 op_sel_hi:[1,0]
	s_waitcnt vmcnt(0)
	v_pk_fma_f32 v[12:13], v[14:15], v[12:13], v[48:49]
	v_pk_fma_f32 v[10:11], v[16:17], v[10:11], v[46:47]
	v_addc_co_u32_e64 v29, s[38:39], -1, v27, s[38:39]
	v_cvt_pk_bf16_f32 v10, v10, v11
	v_cvt_pk_bf16_f32 v11, v12, v13
	global_store_dwordx2 v[28:29], v[10:11], off offset:-3584
	global_load_dwordx4 v[10:13], v[18:19], off offset:2048
	s_nop 0
	global_load_dwordx4 v[14:17], v39, s[64:65]
	global_load_dwordx4 v[42:45], v39, s[72:73]
	v_lshl_add_u64 v[26:27], v[26:27], 0, s[42:43]
	s_waitcnt vmcnt(2)
	v_pk_mul_f32 v[2:3], v[10:11], v[2:3]
	v_pk_mul_f32 v[4:5], v[12:13], v[4:5]
	s_waitcnt vmcnt(1)
	v_pk_add_f32 v[10:11], v[16:17], 1.0 op_sel_hi:[1,0]
	v_pk_add_f32 v[12:13], v[14:15], 1.0 op_sel_hi:[1,0]
	s_waitcnt vmcnt(0)
	v_pk_fma_f32 v[4:5], v[10:11], v[4:5], v[44:45]
	v_pk_fma_f32 v[2:3], v[12:13], v[2:3], v[42:43]
	s_nop 0
	v_cvt_pk_bf16_f32 v2, v2, v3
	v_cvt_pk_bf16_f32 v3, v4, v5
	global_store_dwordx2 v[28:29], v[2:3], off offset:-3072
	global_load_dwordx4 v[2:5], v[18:19], off offset:3072
	s_nop 0
	global_load_dwordx4 v[10:13], v40, s[64:65]
	global_load_dwordx4 v[14:17], v40, s[72:73]
	s_waitcnt vmcnt(2)
	v_pk_mul_f32 v[2:3], v[2:3], v[6:7]
	v_pk_mul_f32 v[4:5], v[4:5], v[8:9]
	s_waitcnt vmcnt(1)
	v_pk_add_f32 v[6:7], v[12:13], 1.0 op_sel_hi:[1,0]
	v_pk_add_f32 v[8:9], v[10:11], 1.0 op_sel_hi:[1,0]
	s_waitcnt vmcnt(0)
	v_pk_fma_f32 v[4:5], v[6:7], v[4:5], v[16:17]
	v_pk_fma_f32 v[2:3], v[8:9], v[2:3], v[14:15]
	s_nop 0
	v_cvt_pk_bf16_f32 v2, v2, v3
	v_cvt_pk_bf16_f32 v3, v4, v5
	global_store_dwordx2 v[28:29], v[2:3], off offset:-2560
	s_cbranch_scc0 .LBB0_1220
